# SSM passes: A^8 table load issued ahead of the fragment staging loads instead of behind the staging's final wait
# speedup vs baseline: 1.0180x; 1.0005x over previous
; #define LAS __attribute__((address_space(3)))
; template <bool PASS2>
; __device__ __forceinline__ void ssm_phase(const Params& p, const Frame& F0) {
;     ...
;         const int g = 4 * (pr & 7) + ((pr >> 3) & 3), subset = pr >> 5;
;         __syncthreads();
;         { const u32x4* src = (const u32x4*)((const bf16_t*)(p.ws + WS_SSMW) + (size_t)g * SSM_FRAG_ELEMS);
;           for (int e = F.tid; e < SSM_FRAG_ELEMS / 8; e += 512) ((LAS u32x4*)F.lds)[e] = src[e];
;           if (F.tid < 64) ((LAS f32x2*)(F.lds + SSM_M1_OFF))[F.tid] = ((const f32x2*)(p.ws + WS_M1))[g * 64 + F.tid]; }
.LBB0_521:
	s_lshr_b32 s24, s23, 3
	s_barrier
	s_and_saveexec_b64 s[16:17], vcc
	s_cbranch_execz .LBB0_524
	s_bfe_u32 s0, s20, 0x30002
	s_and_b32 s1, s24, 3
	s_mul_i32 s0, s0, 0x30000
	s_mul_i32 s1, s1, 0xc000
	s_add_i32 s0, s0, s1
	s_lshl_b32 s10, s0, 1
	v_lshl_add_u64 v[0:1], v[42:43], 0, s[10:11]
	s_mov_b64 s[18:19], 0
	v_mov_b32_e32 v2, v108
	v_mov_b32_e32 v3, v107
	s_lshl_b32 s0, s23, 2
	s_and_b32 s0, s0, 28
	s_and_b32 s1, s24, 3
	s_or_b32 s0, s0, s1
	v_lshl_add_u32 v20, s0, 6, v36
	v_ashrrev_i32_e32 v21, 31, v20
	v_lshl_add_u64 v[20:21], v[20:21], 3, s[12:13]
	global_load_dwordx2 v[20:21], v[20:21], off

; #define LAS __attribute__((address_space(3)))
; template <bool PASS2>
; __device__ __forceinline__ void ssm_phase(const Params& p, const Frame& F0) {
;     ...
;         { const u32x4* src = (const u32x4*)((const bf16_t*)(p.ws + WS_SSMW) + (size_t)g * SSM_FRAG_ELEMS);
;           for (int e = F.tid; e < SSM_FRAG_ELEMS / 8; e += 512) ((LAS u32x4*)F.lds)[e] = src[e];
;           if (F.tid < 64) ((LAS f32x2*)(F.lds + SSM_M1_OFF))[F.tid] = ((const f32x2*)(p.ws + WS_M1))[g * 64 + F.tid]; }
.LBB0_524:
	s_or_b64 exec, exec, s[16:17]
	s_lshl_b32 s0, s23, 2
	s_and_b32 s0, s0, 28
	s_and_b32 s1, s24, 3
	s_or_b32 s16, s0, s1
	s_and_saveexec_b64 s[0:1], s[4:5]
	s_cbranch_execz .LBB0_526
	v_mov_b32_e32 v0, v20
	v_mov_b32_e32 v1, v21
	ds_write_b64 v104, v[0:1]
	v_bfe_u32 v4, v104, 3, 1
	v_lshlrev_b32_e32 v4, 2, v4
	v_sub_u32_e32 v4, v104, v4
	v_mul_f32_e32 v5, v1, v1
	v_add_f32_e32 v6, v0, v0
	v_fma_f32 v7, v0, v0, -v5
	v_mul_f32_e32 v8, v6, v1
	ds_write_b32 v4, v7 offset:512
	ds_write_b32 v4, v8 offset:520
	v_mul_f32_e32 v5, v8, v8
	v_add_f32_e32 v6, v7, v7
	v_fma_f32 v9, v7, v7, -v5
	v_mul_f32_e32 v10, v6, v8
	ds_write_b32 v4, v9 offset:1024
	ds_write_b32 v4, v10 offset:1032
	v_mul_f32_e32 v5, v10, v10
	v_add_f32_e32 v6, v9, v9
	v_fma_f32 v7, v9, v9, -v5
	v_mul_f32_e32 v8, v6, v10
	ds_write_b32 v4, v7 offset:1536
	ds_write_b32 v4, v8 offset:1544
	v_mov_b32_e32 v11, 1.0
	v_mov_b32_e32 v12, 0
	ds_write_b32 v4, v11 offset:10240
	ds_write_b32 v4, v12 offset:10248
	v_mul_f32_e32 v13, v12, v1
	v_mul_f32_e32 v14, v11, v1
	v_fma_f32 v11, v11, v0, -v13
	v_fma_f32 v12, v12, v0, v14
	ds_write_b32 v4, v11 offset:9728
	ds_write_b32 v4, v12 offset:9736
	v_mul_f32_e32 v13, v12, v1
	v_mul_f32_e32 v14, v11, v1
	v_fma_f32 v11, v11, v0, -v13
	v_fma_f32 v12, v12, v0, v14
	ds_write_b32 v4, v11 offset:9216
	ds_write_b32 v4, v12 offset:9224
	v_mul_f32_e32 v13, v12, v1
	v_mul_f32_e32 v14, v11, v1
	v_fma_f32 v11, v11, v0, -v13
	v_fma_f32 v12, v12, v0, v14
	ds_write_b32 v4, v11 offset:8704
	ds_write_b32 v4, v12 offset:8712
	v_mul_f32_e32 v13, v12, v1
	v_mul_f32_e32 v14, v11, v1
	v_fma_f32 v11, v11, v0, -v13
	v_fma_f32 v12, v12, v0, v14
	ds_write_b32 v4, v11 offset:8192
	ds_write_b32 v4, v12 offset:8200
	v_mul_f32_e32 v13, v12, v1
	v_mul_f32_e32 v14, v11, v1
	v_fma_f32 v11, v11, v0, -v13
	v_fma_f32 v12, v12, v0, v14
	ds_write_b32 v4, v11 offset:7680
	ds_write_b32 v4, v12 offset:7688
	v_mul_f32_e32 v13, v12, v1
	v_mul_f32_e32 v14, v11, v1
	v_fma_f32 v11, v11, v0, -v13
	v_fma_f32 v12, v12, v0, v14
	ds_write_b32 v4, v11 offset:7168
	ds_write_b32 v4, v12 offset:7176
	v_mul_f32_e32 v13, v12, v1
	v_mul_f32_e32 v14, v11, v1
	v_fma_f32 v11, v11, v0, -v13
	v_fma_f32 v12, v12, v0, v14
	ds_write_b32 v4, v11 offset:6656
	ds_write_b32 v4, v12 offset:6664
	v_mul_f32_e32 v13, v12, v1
	v_mul_f32_e32 v14, v11, v1
	v_fma_f32 v11, v11, v0, -v13
	v_fma_f32 v12, v12, v0, v14
	ds_write_b32 v4, v11 offset:6144
	ds_write_b32 v4, v12 offset:6152
	v_mul_f32_e32 v13, v12, v1
	v_mul_f32_e32 v14, v11, v1
	v_fma_f32 v11, v11, v0, -v13
	v_fma_f32 v12, v12, v0, v14
	ds_write_b32 v4, v11 offset:5632
	ds_write_b32 v4, v12 offset:5640
	v_mul_f32_e32 v13, v12, v1
	v_mul_f32_e32 v14, v11, v1
	v_fma_f32 v11, v11, v0, -v13
	v_fma_f32 v12, v12, v0, v14
	ds_write_b32 v4, v11 offset:5120
	ds_write_b32 v4, v12 offset:5128
	v_mul_f32_e32 v13, v12, v1
	v_mul_f32_e32 v14, v11, v1
	v_fma_f32 v11, v11, v0, -v13
	v_fma_f32 v12, v12, v0, v14
	ds_write_b32 v4, v11 offset:4608
	ds_write_b32 v4, v12 offset:4616
	v_mul_f32_e32 v13, v12, v1
	v_mul_f32_e32 v14, v11, v1
	v_fma_f32 v11, v11, v0, -v13
	v_fma_f32 v12, v12, v0, v14
	ds_write_b32 v4, v11 offset:4096
	ds_write_b32 v4, v12 offset:4104
	v_mul_f32_e32 v13, v12, v1
	v_mul_f32_e32 v14, v11, v1
	v_fma_f32 v11, v11, v0, -v13
	v_fma_f32 v12, v12, v0, v14
	ds_write_b32 v4, v11 offset:3584
	ds_write_b32 v4, v12 offset:3592
	v_mul_f32_e32 v13, v12, v1
	v_mul_f32_e32 v14, v11, v1
	v_fma_f32 v11, v11, v0, -v13
	v_fma_f32 v12, v12, v0, v14
	ds_write_b32 v4, v11 offset:3072
	ds_write_b32 v4, v12 offset:3080
	v_mul_f32_e32 v13, v12, v1
	v_mul_f32_e32 v14, v11, v1
	v_fma_f32 v11, v11, v0, -v13
	v_fma_f32 v12, v12, v0, v14
	ds_write_b32 v4, v11 offset:2560
	ds_write_b32 v4, v12 offset:2568
	v_mul_f32_e32 v13, v12, v1
	v_mul_f32_e32 v14, v11, v1
	v_fma_f32 v11, v11, v0, -v13
	v_fma_f32 v12, v12, v0, v14
	ds_write_b32 v4, v11 offset:2048
	ds_write_b32 v4, v12 offset:2056

; #define LAS __attribute__((address_space(3)))
; template <bool PASS2>
; __device__ __forceinline__ void ssm_phase(const Params& p, const Frame& F0) {
;     ...
;         const int g = 4 * (pr & 7) + ((pr >> 3) & 3), subset = pr >> 5;
;         __syncthreads();
;         { const u32x4* src = (const u32x4*)((const bf16_t*)(p.ws + WS_SSMW) + (size_t)g * SSM_FRAG_ELEMS);
;           for (int e = F.tid; e < SSM_FRAG_ELEMS / 8; e += 512) ((LAS u32x4*)F.lds)[e] = src[e];
;           if (F.tid < 64) ((LAS f32x2*)(F.lds + SSM_M1_OFF))[F.tid] = ((const f32x2*)(p.ws + WS_M1))[g * 64 + F.tid]; }
.LBB0_607:
	s_lshr_b32 s3, s90, 3
	s_barrier
	s_and_saveexec_b64 s[16:17], s[4:5]
	s_cbranch_execz .LBB0_610
	s_bfe_u32 s0, s80, 0x30002
	s_and_b32 s18, s3, 3
	s_mul_i32 s0, s0, 0x30000
	s_mul_i32 s18, s18, 0xc000
	s_add_i32 s0, s0, s18
	s_lshl_b32 s0, s0, 1
	v_lshl_add_u64 v[2:3], v[112:113], 0, s[0:1]
	s_lshl_b32 s18, s90, 2
	s_and_b32 s18, s18, 28
	s_and_b32 s19, s3, 3
	s_or_b32 s18, s18, s19
	v_lshl_add_u32 v22, s18, 6, v92
	v_ashrrev_i32_e32 v23, 31, v22
	v_lshl_add_u64 v[22:23], v[22:23], 3, s[68:69]
	global_load_dwordx2 v[22:23], v[22:23], off
	s_mov_b64 s[18:19], 0
	v_mov_b32_e32 v1, v197
	v_mov_b32_e32 v20, v196

; #define LAS __attribute__((address_space(3)))
; template <bool PASS2>
; __device__ __forceinline__ void ssm_phase(const Params& p, const Frame& F0) {
;     ...
;         { const u32x4* src = (const u32x4*)((const bf16_t*)(p.ws + WS_SSMW) + (size_t)g * SSM_FRAG_ELEMS);
;           for (int e = F.tid; e < SSM_FRAG_ELEMS / 8; e += 512) ((LAS u32x4*)F.lds)[e] = src[e];
;           if (F.tid < 64) ((LAS f32x2*)(F.lds + SSM_M1_OFF))[F.tid] = ((const f32x2*)(p.ws + WS_M1))[g * 64 + F.tid]; }
.LBB0_610:
	s_or_b64 exec, exec, s[16:17]
	s_lshl_b32 s0, s90, 2
	s_and_b32 s0, s0, 28
	s_and_b32 s3, s3, 3
	s_or_b32 s3, s0, s3
	s_and_saveexec_b64 s[16:17], s[6:7]
	s_cbranch_execz .LBB0_612
	v_mov_b32_e32 v2, v22
	v_mov_b32_e32 v3, v23
	ds_write_b64 v103, v[2:3]
	v_bfe_u32 v26, v103, 3, 1
	v_lshlrev_b32_e32 v26, 2, v26
	v_sub_u32_e32 v26, v103, v26
	v_mul_f32_e32 v27, v3, v3
	v_add_f32_e32 v28, v2, v2
	v_fma_f32 v29, v2, v2, -v27
	v_mul_f32_e32 v30, v28, v3
	ds_write_b32 v26, v29 offset:512
	ds_write_b32 v26, v30 offset:520
	v_mul_f32_e32 v27, v30, v30
	v_add_f32_e32 v28, v29, v29
	v_fma_f32 v31, v29, v29, -v27
	v_mul_f32_e32 v32, v28, v30
	ds_write_b32 v26, v31 offset:1024
	ds_write_b32 v26, v32 offset:1032
	v_mul_f32_e32 v27, v32, v32
	v_add_f32_e32 v28, v31, v31
	v_fma_f32 v29, v31, v31, -v27
	v_mul_f32_e32 v30, v28, v32
	ds_write_b32 v26, v29 offset:1536
	ds_write_b32 v26, v30 offset:1544
